# combo18: combo17 + P1 epilogue: the eight per-row-group rss loads issued together before the first group instead of one load + full wait per group
# speedup vs baseline: 1.0004x; 1.0004x over previous
; __device__ __forceinline__ unsigned cvt_pk_bf16(float lo, float hi) { unsigned r; asm volatile("v_cvt_pk_bf16_f32 %0, %1, %2" : "=v"(r) : "v"(lo), "v"(hi)); return r; }
;     __device__ __forceinline__ void operator()(const f32x4 (&acc)[2][2][4][2], const Unit& u, int wr, int wc, int fr, int fq) const {
;     ...
;             for (int m = 0; m < 4; ++m) { bf16_t* rowp = base + (size_t)(row0 + ai * HALF + m * 16) * ldc + col0;
;                 const float rs = rowss ? __builtin_amdgcn_rsqf(rowss[row0 + ai * HALF + m * 16] * (1.0f / 1024.0f) + 1e-6f) : 1.0f;
; #pragma unroll
;                 for (int bj = 0; bj < 2; ++bj) { f32x4 v0 = acc[ai][bj][m][0] * rs + bv[bj][0], v1 = acc[ai][bj][m][1] * rs + bv[bj][1];
;                     if (ACT == 1) { f32x2 a = gelu_pk((f32x2){v0[0], v0[1]}), b = gelu_pk((f32x2){v0[2], v0[3]}), c = gelu_pk((f32x2){v1[0], v1[1]}), d = gelu_pk((f32x2){v1[2], v1[3]});
;                         v0 = (f32x4){a.x, a.y, b.x, b.y}; v1 = (f32x4){c.x, c.y, d.x, d.y}; }
;                     if (ACT == 2) { v0 = __builtin_elementwise_max(v0, (f32x4){0.f, 0.f, 0.f, 0.f}); v1 = __builtin_elementwise_max(v1, (f32x4){0.f, 0.f, 0.f, 0.f}); v0 = v0 * v0; v1 = v1 * v1; }
;                     v0 = v0 * sc; v1 = v1 * sc; u32x4 w; w.x = cvt_pk_bf16(v0[0], v0[1]); w.y = cvt_pk_bf16(v0[2], v0[3]); w.z = cvt_pk_bf16(v1[0], v1[1]); w.w = cvt_pk_bf16(v1[2], v1[3]);
;                     *(u32x4*)(rowp + bj * HALF) = w; } }
.LBB0_223:
	v_lshl_add_u32 v156, s31, 8, v167
	v_readlane_b32 s18, v254, 57
	v_ashrrev_i32_e32 v157, 31, v156
	v_cndmask_b32_e64 v154, 0, 1, s[82:83]
	v_readlane_b32 s19, v254, 58
	v_mov_b32_e32 v166, 1.0
	v_cmp_ne_u32_e64 s[2:3], 1, v154
	s_andn2_b64 vcc, exec, s[82:83]
	v_lshl_add_u64 v[154:155], v[156:157], 2, s[18:19]
	v_mov_b32_e32 v168, 1.0
	s_cbranch_vccnz .LBB0_225
	global_load_dword v234, v[154:155], off
	global_load_dword v235, v[154:155], off offset:64
	global_load_dword v236, v[154:155], off offset:128
	global_load_dword v237, v[154:155], off offset:192
	global_load_dword v238, v[154:155], off offset:512
	global_load_dword v239, v[154:155], off offset:576
	global_load_dword v240, v[154:155], off offset:640
	global_load_dword v241, v[154:155], off offset:704
	s_waitcnt vmcnt(0)
	v_fmamk_f32 v162, v234, 0x3a800000, v199
	v_rsq_f32_e32 v168, v162
.LBB0_225:
	v_lshl_add_u64 v[158:159], v[158:159], 1, s[60:61]
	v_lshlrev_b64 v[162:163], 12, v[156:157]
	v_lshl_add_u64 v[162:163], v[158:159], 0, v[162:163]
	s_waitcnt vmcnt(0)
	v_pk_fma_f32 v[126:127], v[126:127], v[168:169], v[134:135] op_sel_hi:[1,0,1]
	v_pk_fma_f32 v[124:125], v[124:125], v[168:169], v[132:133] op_sel_hi:[1,0,1]
	v_pk_fma_f32 v[164:165], v[122:123], v[168:169], v[130:131] op_sel_hi:[1,0,1]
	v_pk_fma_f32 v[122:123], v[120:121], v[168:169], v[128:129] op_sel_hi:[1,0,1]
	v_cvt_pk_bf16_f32 v120, v124, v125
	v_cvt_pk_bf16_f32 v121, v126, v127
	s_and_b64 vcc, exec, s[2:3]
	v_cvt_pk_bf16_f32 v122, v122, v123
	v_cvt_pk_bf16_f32 v123, v164, v165
	global_store_dwordx4 v[162:163], v[120:123], off
	v_pk_fma_f32 v[118:119], v[118:119], v[168:169], v[142:143] op_sel_hi:[1,0,1]
	v_pk_fma_f32 v[116:117], v[116:117], v[168:169], v[140:141] op_sel_hi:[1,0,1]
	v_pk_fma_f32 v[120:121], v[114:115], v[168:169], v[138:139] op_sel_hi:[1,0,1]
	v_pk_fma_f32 v[114:115], v[112:113], v[168:169], v[136:137] op_sel_hi:[1,0,1]
	v_cvt_pk_bf16_f32 v112, v116, v117
	v_cvt_pk_bf16_f32 v113, v118, v119
	s_nop 0
	v_cvt_pk_bf16_f32 v114, v114, v115
	v_cvt_pk_bf16_f32 v115, v120, v121
	global_store_dwordx4 v[162:163], v[112:115], off offset:256
	s_cbranch_vccnz .LBB0_227
	s_nop 1
	v_fmamk_f32 v112, v235, 0x3a800000, v199
	v_rsq_f32_e32 v166, v112
.LBB0_227:
	s_nop 0
	v_or_b32_e32 v112, 16, v156
	v_ashrrev_i32_e32 v113, 31, v112
	v_lshlrev_b64 v[112:113], 12, v[112:113]
	v_lshl_add_u64 v[112:113], v[158:159], 0, v[112:113]
	v_pk_fma_f32 v[110:111], v[110:111], v[166:167], v[134:135] op_sel_hi:[1,0,1]
	v_pk_fma_f32 v[108:109], v[108:109], v[166:167], v[132:133] op_sel_hi:[1,0,1]
	v_pk_fma_f32 v[114:115], v[106:107], v[166:167], v[130:131] op_sel_hi:[1,0,1]
	v_pk_fma_f32 v[106:107], v[104:105], v[166:167], v[128:129] op_sel_hi:[1,0,1]
	v_cvt_pk_bf16_f32 v104, v108, v109
	v_cvt_pk_bf16_f32 v105, v110, v111
	v_pk_fma_f32 v[102:103], v[102:103], v[166:167], v[142:143] op_sel_hi:[1,0,1]
	v_cvt_pk_bf16_f32 v106, v106, v107
	v_cvt_pk_bf16_f32 v107, v114, v115
	global_store_dwordx4 v[112:113], v[104:107], off
	v_pk_fma_f32 v[100:101], v[100:101], v[166:167], v[140:141] op_sel_hi:[1,0,1]
	s_and_b64 vcc, exec, s[2:3]
	v_pk_fma_f32 v[104:105], v[98:99], v[166:167], v[138:139] op_sel_hi:[1,0,1]
	v_pk_fma_f32 v[98:99], v[96:97], v[166:167], v[136:137] op_sel_hi:[1,0,1]
	v_cvt_pk_bf16_f32 v96, v100, v101
	v_cvt_pk_bf16_f32 v97, v102, v103
	s_nop 0
	v_cvt_pk_bf16_f32 v98, v98, v99
	v_cvt_pk_bf16_f32 v99, v104, v105
	global_store_dwordx4 v[112:113], v[96:99], off offset:256
	s_nop 1
	v_mov_b32_e32 v96, 1.0
	v_mov_b32_e32 v98, 1.0
	s_cbranch_vccnz .LBB0_229
	s_nop 1
	v_fmamk_f32 v97, v236, 0x3a800000, v199
	v_rsq_f32_e32 v98, v97
.LBB0_229:
	v_or_b32_e32 v100, 32, v156
	v_ashrrev_i32_e32 v101, 31, v100
	v_lshlrev_b64 v[100:101], 12, v[100:101]
	v_lshl_add_u64 v[100:101], v[158:159], 0, v[100:101]
	v_pk_fma_f32 v[94:95], v[94:95], v[98:99], v[134:135] op_sel_hi:[1,0,1]
	v_pk_fma_f32 v[92:93], v[92:93], v[98:99], v[132:133] op_sel_hi:[1,0,1]
	v_pk_fma_f32 v[102:103], v[90:91], v[98:99], v[130:131] op_sel_hi:[1,0,1]
	v_pk_fma_f32 v[90:91], v[88:89], v[98:99], v[128:129] op_sel_hi:[1,0,1]
	v_cvt_pk_bf16_f32 v88, v92, v93
	v_cvt_pk_bf16_f32 v89, v94, v95
	s_and_b64 vcc, exec, s[2:3]
	v_cvt_pk_bf16_f32 v90, v90, v91
	v_cvt_pk_bf16_f32 v91, v102, v103
	global_store_dwordx4 v[100:101], v[88:91], off
	v_pk_fma_f32 v[86:87], v[86:87], v[98:99], v[142:143] op_sel_hi:[1,0,1]
	v_pk_fma_f32 v[84:85], v[84:85], v[98:99], v[140:141] op_sel_hi:[1,0,1]
	v_pk_fma_f32 v[88:89], v[82:83], v[98:99], v[138:139] op_sel_hi:[1,0,1]
	v_pk_fma_f32 v[82:83], v[80:81], v[98:99], v[136:137] op_sel_hi:[1,0,1]
	v_cvt_pk_bf16_f32 v80, v84, v85
	v_cvt_pk_bf16_f32 v81, v86, v87
	s_nop 0
	v_cvt_pk_bf16_f32 v82, v82, v83
	v_cvt_pk_bf16_f32 v83, v88, v89
	global_store_dwordx4 v[100:101], v[80:83], off offset:256
	s_cbranch_vccnz .LBB0_231
	s_nop 1
	v_fmamk_f32 v80, v237, 0x3a800000, v199
	v_rsq_f32_e32 v96, v80
; __device__ __forceinline__ unsigned cvt_pk_bf16(float lo, float hi) { unsigned r; asm volatile("v_cvt_pk_bf16_f32 %0, %1, %2" : "=v"(r) : "v"(lo), "v"(hi)); return r; }
;     __device__ __forceinline__ void operator()(const f32x4 (&acc)[2][2][4][2], const Unit& u, int wr, int wc, int fr, int fq) const {
;     ...
;             for (int m = 0; m < 4; ++m) { bf16_t* rowp = base + (size_t)(row0 + ai * HALF + m * 16) * ldc + col0;
;                 const float rs = rowss ? __builtin_amdgcn_rsqf(rowss[row0 + ai * HALF + m * 16] * (1.0f / 1024.0f) + 1e-6f) : 1.0f;
; #pragma unroll
;                 for (int bj = 0; bj < 2; ++bj) { f32x4 v0 = acc[ai][bj][m][0] * rs + bv[bj][0], v1 = acc[ai][bj][m][1] * rs + bv[bj][1];
;                     if (ACT == 1) { f32x2 a = gelu_pk((f32x2){v0[0], v0[1]}), b = gelu_pk((f32x2){v0[2], v0[3]}), c = gelu_pk((f32x2){v1[0], v1[1]}), d = gelu_pk((f32x2){v1[2], v1[3]});
;                         v0 = (f32x4){a.x, a.y, b.x, b.y}; v1 = (f32x4){c.x, c.y, d.x, d.y}; }
;                     if (ACT == 2) { v0 = __builtin_elementwise_max(v0, (f32x4){0.f, 0.f, 0.f, 0.f}); v1 = __builtin_elementwise_max(v1, (f32x4){0.f, 0.f, 0.f, 0.f}); v0 = v0 * v0; v1 = v1 * v1; }
;                     v0 = v0 * sc; v1 = v1 * sc; u32x4 w; w.x = cvt_pk_bf16(v0[0], v0[1]); w.y = cvt_pk_bf16(v0[2], v0[3]); w.z = cvt_pk_bf16(v1[0], v1[1]); w.w = cvt_pk_bf16(v1[2], v1[3]);
;                     *(u32x4*)(rowp + bj * HALF) = w; } }
.LBB0_231:
	s_nop 0
	v_or_b32_e32 v80, 48, v156
	v_ashrrev_i32_e32 v81, 31, v80
	v_lshlrev_b64 v[80:81], 12, v[80:81]
	v_lshl_add_u64 v[80:81], v[158:159], 0, v[80:81]
	v_pk_fma_f32 v[78:79], v[78:79], v[96:97], v[134:135] op_sel_hi:[1,0,1]
	v_pk_fma_f32 v[76:77], v[76:77], v[96:97], v[132:133] op_sel_hi:[1,0,1]
	v_pk_fma_f32 v[82:83], v[74:75], v[96:97], v[130:131] op_sel_hi:[1,0,1]
	v_pk_fma_f32 v[74:75], v[72:73], v[96:97], v[128:129] op_sel_hi:[1,0,1]
	v_cvt_pk_bf16_f32 v72, v76, v77
	v_cvt_pk_bf16_f32 v73, v78, v79
	v_pk_fma_f32 v[68:69], v[68:69], v[96:97], v[140:141] op_sel_hi:[1,0,1]
	v_cvt_pk_bf16_f32 v74, v74, v75
	v_cvt_pk_bf16_f32 v75, v82, v83
	global_store_dwordx4 v[80:81], v[72:75], off
	v_pk_fma_f32 v[70:71], v[70:71], v[96:97], v[142:143] op_sel_hi:[1,0,1]
	s_and_b64 vcc, exec, s[2:3]
	v_pk_fma_f32 v[72:73], v[66:67], v[96:97], v[138:139] op_sel_hi:[1,0,1]
	v_pk_fma_f32 v[66:67], v[64:65], v[96:97], v[136:137] op_sel_hi:[1,0,1]
	v_cvt_pk_bf16_f32 v64, v68, v69
	v_cvt_pk_bf16_f32 v65, v70, v71
	v_mov_b32_e32 v68, 1.0
	v_cvt_pk_bf16_f32 v66, v66, v67
	v_cvt_pk_bf16_f32 v67, v72, v73
	global_store_dwordx4 v[80:81], v[64:67], off offset:256
	s_nop 1
	v_mov_b32_e32 v64, 1.0
	s_cbranch_vccnz .LBB0_233
	s_nop 1
	v_fmamk_f32 v65, v238, 0x3a800000, v199
	v_rsq_f32_e32 v68, v65
.LBB0_233:
	v_lshlrev_b64 v[66:67], 12, v[156:157]
	v_lshl_add_u64 v[66:67], v[158:159], 0, v[66:67]
	v_pk_fma_f32 v[60:61], v[60:61], v[68:69], v[132:133] op_sel_hi:[1,0,1]
	s_mov_b32 s11, 0x80000
	v_pk_fma_f32 v[72:73], v[58:59], v[68:69], v[130:131] op_sel_hi:[1,0,1]
	v_pk_fma_f32 v[58:59], v[56:57], v[68:69], v[128:129] op_sel_hi:[1,0,1]
	v_cvt_pk_bf16_f32 v56, v60, v61
	v_add_co_u32_e32 v60, vcc, s11, v66
	s_mov_b64 s[18:19], 0x80000
	v_pk_fma_f32 v[62:63], v[62:63], v[68:69], v[134:135] op_sel_hi:[1,0,1]
	v_addc_co_u32_e32 v61, vcc, 0, v67, vcc
	v_cvt_pk_bf16_f32 v57, v62, v63
	v_lshl_add_u64 v[70:71], v[66:67], 0, s[18:19]
	v_cvt_pk_bf16_f32 v58, v58, v59
	v_cvt_pk_bf16_f32 v59, v72, v73
	global_store_dwordx4 v[60:61], v[56:59], off
	s_and_b64 vcc, exec, s[2:3]
	v_pk_fma_f32 v[54:55], v[54:55], v[68:69], v[142:143] op_sel_hi:[1,0,1]
	v_pk_fma_f32 v[56:57], v[50:51], v[68:69], v[138:139] op_sel_hi:[1,0,1]
	v_pk_fma_f32 v[50:51], v[48:49], v[68:69], v[136:137] op_sel_hi:[1,0,1]
	v_pk_fma_f32 v[52:53], v[52:53], v[68:69], v[140:141] op_sel_hi:[1,0,1]
	s_nop 0
	v_cvt_pk_bf16_f32 v48, v52, v53
	v_cvt_pk_bf16_f32 v49, v54, v55
	v_cvt_pk_bf16_f32 v50, v50, v51
	v_cvt_pk_bf16_f32 v51, v56, v57
	global_store_dwordx4 v[70:71], v[48:51], off offset:256
	s_cbranch_vccnz .LBB0_235
	s_nop 1
	v_fmamk_f32 v48, v239, 0x3a800000, v199
	v_rsq_f32_e32 v64, v48
.LBB0_235:
	s_nop 0
	v_pk_fma_f32 v[44:45], v[44:45], v[64:65], v[132:133] op_sel_hi:[1,0,1]
	s_mov_b32 s11, 0x90000
	v_pk_fma_f32 v[50:51], v[42:43], v[64:65], v[130:131] op_sel_hi:[1,0,1]
	v_pk_fma_f32 v[42:43], v[40:41], v[64:65], v[128:129] op_sel_hi:[1,0,1]
	v_cvt_pk_bf16_f32 v40, v44, v45
	v_add_co_u32_e32 v44, vcc, s11, v66
	s_mov_b64 s[18:19], 0x90000
	v_pk_fma_f32 v[46:47], v[46:47], v[64:65], v[134:135] op_sel_hi:[1,0,1]
	v_addc_co_u32_e32 v45, vcc, 0, v67, vcc
	v_cvt_pk_bf16_f32 v41, v46, v47
	v_lshl_add_u64 v[48:49], v[66:67], 0, s[18:19]
	v_cvt_pk_bf16_f32 v42, v42, v43
	v_cvt_pk_bf16_f32 v43, v50, v51
	global_store_dwordx4 v[44:45], v[40:43], off
	v_pk_fma_f32 v[36:37], v[36:37], v[64:65], v[140:141] op_sel_hi:[1,0,1]
	v_pk_fma_f32 v[38:39], v[38:39], v[64:65], v[142:143] op_sel_hi:[1,0,1]
	v_pk_fma_f32 v[40:41], v[34:35], v[64:65], v[138:139] op_sel_hi:[1,0,1]
	v_pk_fma_f32 v[34:35], v[32:33], v[64:65], v[136:137] op_sel_hi:[1,0,1]
	v_cvt_pk_bf16_f32 v32, v36, v37
	v_cvt_pk_bf16_f32 v33, v38, v39
	s_and_b64 vcc, exec, s[2:3]
	v_cvt_pk_bf16_f32 v34, v34, v35
	v_cvt_pk_bf16_f32 v35, v40, v41
	global_store_dwordx4 v[48:49], v[32:35], off offset:256
	v_mov_b32_e32 v36, 1.0
	s_nop 0
	v_mov_b32_e32 v32, 1.0
	s_cbranch_vccnz .LBB0_237
	s_nop 1
	v_fmamk_f32 v33, v240, 0x3a800000, v199
	v_rsq_f32_e32 v36, v33
.LBB0_237:
	v_lshlrev_b64 v[34:35], 12, v[156:157]
	v_lshl_add_u64 v[34:35], v[158:159], 0, v[34:35]
	v_pk_fma_f32 v[28:29], v[28:29], v[36:37], v[132:133] op_sel_hi:[1,0,1]
	s_mov_b32 s11, 0xa0000
	v_pk_fma_f32 v[40:41], v[26:27], v[36:37], v[130:131] op_sel_hi:[1,0,1]
	v_pk_fma_f32 v[26:27], v[24:25], v[36:37], v[128:129] op_sel_hi:[1,0,1]
	v_cvt_pk_bf16_f32 v24, v28, v29
	v_add_co_u32_e32 v28, vcc, s11, v34
	s_mov_b64 s[18:19], 0xa0000
	v_pk_fma_f32 v[30:31], v[30:31], v[36:37], v[134:135] op_sel_hi:[1,0,1]
	v_addc_co_u32_e32 v29, vcc, 0, v35, vcc
	v_cvt_pk_bf16_f32 v25, v30, v31
	v_lshl_add_u64 v[38:39], v[34:35], 0, s[18:19]
	v_cvt_pk_bf16_f32 v26, v26, v27
	v_cvt_pk_bf16_f32 v27, v40, v41
	global_store_dwordx4 v[28:29], v[24:27], off
	s_and_b64 vcc, exec, s[2:3]
	v_pk_fma_f32 v[22:23], v[22:23], v[36:37], v[142:143] op_sel_hi:[1,0,1]
	v_pk_fma_f32 v[24:25], v[18:19], v[36:37], v[138:139] op_sel_hi:[1,0,1]
	v_pk_fma_f32 v[18:19], v[16:17], v[36:37], v[136:137] op_sel_hi:[1,0,1]
	v_pk_fma_f32 v[20:21], v[20:21], v[36:37], v[140:141] op_sel_hi:[1,0,1]
	s_nop 0
	v_cvt_pk_bf16_f32 v16, v20, v21
	v_cvt_pk_bf16_f32 v17, v22, v23
	v_cvt_pk_bf16_f32 v18, v18, v19
	v_cvt_pk_bf16_f32 v19, v24, v25
	global_store_dwordx4 v[38:39], v[16:19], off offset:256
	s_cbranch_vccnz .LBB0_239
	s_nop 1
	v_fmamk_f32 v16, v241, 0x3a800000, v199
	v_rsq_f32_e32 v32, v16
